# P8 row statistics via last-trip prefetch + LDS table, last-trip waits count the two extra loads (vmcnt 10)
# baseline (speedup 1.0000x reference)
.Lmy_p8_noload:
	s_add_i32 s70, s57, s45
	v_lshl_add_u64 v[138:139], s[6:7], 0, v[132:133]
	s_mov_b32 m0, s70
	ds_read_b128 v[188:191], v155 offset:16384
	ds_read_b128 v[192:195], v155 offset:17408
	ds_read_b128 v[196:199], v155 offset:18432
	ds_read_b128 v[200:203], v155 offset:19456
	ds_read_b128 v[204:207], v155 offset:20480
	ds_read_b128 v[208:211], v155 offset:21504
	ds_read_b128 v[212:215], v155 offset:22528
	ds_read_b128 v[216:219], v155 offset:23552
	global_load_lds_dwordx4 v[138:139], off
	s_add_i32 m0, s70, 0x2000
	s_add_u32 s70, s6, 0x10000
	v_lshl_add_u64 v[220:221], s[6:7], 0, v[136:137]
	s_addc_u32 s71, s7, 0
	s_add_i32 s72, s58, s45
	global_load_lds_dwordx4 v[220:221], off
	v_lshl_add_u64 v[222:223], s[70:71], 0, v[132:133]
	s_mov_b32 m0, s72
	v_lshl_add_u64 v[224:225], s[8:9], 0, v[134:135]
	global_load_lds_dwordx4 v[222:223], off
	v_lshl_add_u64 v[222:223], s[70:71], 0, v[136:137]
	s_add_i32 m0, s72, 0x2000
	s_nop 0
	global_load_lds_dwordx4 v[222:223], off
	v_lshl_add_u64 v[222:223], s[8:9], 0, v[130:131]
	s_mov_b32 m0, s46
	s_nop 0
	global_load_lds_dwordx4 v[222:223], off
	s_mov_b32 m0, s47
	s_nop 0
	global_load_lds_dwordx4 v[224:225], off
	s_cmp_lg_u32 s12, s0
	s_cbranch_scc1 .Lmy_p8_w8b
	s_waitcnt vmcnt(10)
	s_branch .Lmy_p8_wdb
.Lmy_p8_w8b:
	s_waitcnt vmcnt(8)
.Lmy_p8_wdb:
	s_waitcnt lgkmcnt(0)
	s_barrier
	s_setprio 1
	s_waitcnt lgkmcnt(0)
	v_mfma_f32_16x16x32_bf16 v[62:65], v[156:159], v[188:191], v[62:65]
	v_mfma_f32_16x16x32_bf16 v[58:61], v[164:167], v[188:191], v[58:61]
	v_mfma_f32_16x16x32_bf16 v[46:49], v[156:159], v[196:199], v[46:49]
	v_mfma_f32_16x16x32_bf16 v[42:45], v[164:167], v[196:199], v[42:45]
	v_mfma_f32_16x16x32_bf16 v[30:33], v[156:159], v[204:207], v[30:33]
	v_mfma_f32_16x16x32_bf16 v[26:29], v[164:167], v[204:207], v[26:29]
	v_mfma_f32_16x16x32_bf16 v[14:17], v[156:159], v[212:215], v[14:17]
	v_mfma_f32_16x16x32_bf16 v[10:13], v[164:167], v[212:215], v[10:13]
	v_mfma_f32_16x16x32_bf16 v[62:65], v[160:163], v[192:195], v[62:65]
	v_mfma_f32_16x16x32_bf16 v[58:61], v[168:171], v[192:195], v[58:61]
	v_mfma_f32_16x16x32_bf16 v[46:49], v[160:163], v[200:203], v[46:49]
	v_mfma_f32_16x16x32_bf16 v[42:45], v[168:171], v[200:203], v[42:45]
	v_mfma_f32_16x16x32_bf16 v[30:33], v[160:163], v[208:211], v[30:33]
	v_mfma_f32_16x16x32_bf16 v[26:29], v[168:171], v[208:211], v[26:29]
	v_mfma_f32_16x16x32_bf16 v[14:17], v[160:163], v[216:219], v[14:17]
	v_mfma_f32_16x16x32_bf16 v[10:13], v[168:171], v[216:219], v[10:13]
	s_setprio 0
	s_setprio 1
	v_mfma_f32_16x16x32_bf16 v[54:57], v[172:175], v[188:191], v[54:57]
	v_mfma_f32_16x16x32_bf16 v[50:53], v[180:183], v[188:191], v[50:53]
	v_mfma_f32_16x16x32_bf16 v[38:41], v[172:175], v[196:199], v[38:41]
	v_mfma_f32_16x16x32_bf16 v[34:37], v[180:183], v[196:199], v[34:37]
	v_mfma_f32_16x16x32_bf16 v[22:25], v[172:175], v[204:207], v[22:25]
	v_mfma_f32_16x16x32_bf16 v[18:21], v[180:183], v[204:207], v[18:21]
	v_mfma_f32_16x16x32_bf16 v[6:9], v[172:175], v[212:215], v[6:9]
	v_mfma_f32_16x16x32_bf16 v[2:5], v[180:183], v[212:215], v[2:5]
	v_mfma_f32_16x16x32_bf16 v[54:57], v[176:179], v[192:195], v[54:57]
	v_mfma_f32_16x16x32_bf16 v[50:53], v[184:187], v[192:195], v[50:53]
	v_mfma_f32_16x16x32_bf16 v[38:41], v[176:179], v[200:203], v[38:41]
	v_mfma_f32_16x16x32_bf16 v[34:37], v[184:187], v[200:203], v[34:37]
	v_mfma_f32_16x16x32_bf16 v[22:25], v[176:179], v[208:211], v[22:25]
	v_mfma_f32_16x16x32_bf16 v[18:21], v[184:187], v[208:211], v[18:21]
	v_mfma_f32_16x16x32_bf16 v[6:9], v[176:179], v[216:219], v[6:9]
	v_mfma_f32_16x16x32_bf16 v[2:5], v[184:187], v[216:219], v[2:5]
	s_setprio 0
	s_barrier
	s_add_i32 s70, 0, 0x18000
	v_add_u32_e32 v146, s70, v149
	s_add_i32 s71, 0, 0x1c000
	ds_read_b128 v[156:159], v146
	ds_read_b128 v[160:163], v146 offset:1024
	ds_read_b128 v[164:167], v146 offset:2048
	ds_read_b128 v[168:171], v146 offset:3072
	v_add_u32_e32 v146, s71, v149
	ds_read_b128 v[172:175], v146
	ds_read_b128 v[176:179], v146 offset:1024
	ds_read_b128 v[180:183], v146 offset:2048
	ds_read_b128 v[184:187], v146 offset:3072
	s_add_u32 s8, s8, 0x40000
	s_addc_u32 s9, s9, 0
	s_mov_b32 m0, s48
	v_lshl_add_u64 v[226:227], s[8:9], 0, v[130:131]
	ds_read_b128 v[188:191], v155 offset:32768
	ds_read_b128 v[192:195], v155 offset:33792
	ds_read_b128 v[196:199], v155 offset:34816
	ds_read_b128 v[200:203], v155 offset:35840
	ds_read_b128 v[204:207], v155 offset:36864
	ds_read_b128 v[208:211], v155 offset:37888
	ds_read_b128 v[212:215], v155 offset:38912
	ds_read_b128 v[216:219], v155 offset:39936
	global_load_lds_dwordx4 v[226:227], off
	v_lshl_add_u64 v[226:227], s[8:9], 0, v[134:135]
	s_mov_b32 m0, s49
	s_nop 0
	global_load_lds_dwordx4 v[226:227], off
	s_cmp_lg_u32 s12, s0
	s_cbranch_scc1 .Lmy_p8_w8c
	s_waitcnt vmcnt(10)
	s_branch .Lmy_p8_wdc

.Lmy_p8_wdc:
	s_waitcnt lgkmcnt(0)
	s_barrier
	s_setprio 1
	s_waitcnt lgkmcnt(0)
	v_mfma_f32_16x16x32_bf16 v[126:129], v[156:159], v[188:191], v[126:129]
	v_mfma_f32_16x16x32_bf16 v[122:125], v[164:167], v[188:191], v[122:125]
	v_mfma_f32_16x16x32_bf16 v[110:113], v[156:159], v[196:199], v[110:113]
	v_mfma_f32_16x16x32_bf16 v[106:109], v[164:167], v[196:199], v[106:109]
	v_mfma_f32_16x16x32_bf16 v[94:97], v[156:159], v[204:207], v[94:97]
	v_mfma_f32_16x16x32_bf16 v[90:93], v[164:167], v[204:207], v[90:93]
	v_mfma_f32_16x16x32_bf16 v[78:81], v[156:159], v[212:215], v[78:81]
	v_mfma_f32_16x16x32_bf16 v[74:77], v[164:167], v[212:215], v[74:77]
	v_mfma_f32_16x16x32_bf16 v[126:129], v[160:163], v[192:195], v[126:129]
	v_mfma_f32_16x16x32_bf16 v[122:125], v[168:171], v[192:195], v[122:125]
	v_mfma_f32_16x16x32_bf16 v[110:113], v[160:163], v[200:203], v[110:113]
	v_mfma_f32_16x16x32_bf16 v[106:109], v[168:171], v[200:203], v[106:109]
	v_mfma_f32_16x16x32_bf16 v[94:97], v[160:163], v[208:211], v[94:97]
	v_mfma_f32_16x16x32_bf16 v[90:93], v[168:171], v[208:211], v[90:93]
	v_mfma_f32_16x16x32_bf16 v[78:81], v[160:163], v[216:219], v[78:81]
	v_mfma_f32_16x16x32_bf16 v[74:77], v[168:171], v[216:219], v[74:77]
	s_setprio 0
	s_setprio 1
	v_mfma_f32_16x16x32_bf16 v[118:121], v[172:175], v[188:191], v[118:121]
	v_mfma_f32_16x16x32_bf16 v[114:117], v[180:183], v[188:191], v[114:117]
	v_mfma_f32_16x16x32_bf16 v[102:105], v[172:175], v[196:199], v[102:105]
	v_mfma_f32_16x16x32_bf16 v[98:101], v[180:183], v[196:199], v[98:101]
	v_mfma_f32_16x16x32_bf16 v[86:89], v[172:175], v[204:207], v[86:89]
	v_mfma_f32_16x16x32_bf16 v[82:85], v[180:183], v[204:207], v[82:85]
	v_mfma_f32_16x16x32_bf16 v[70:73], v[172:175], v[212:215], v[70:73]
	v_mfma_f32_16x16x32_bf16 v[66:69], v[180:183], v[212:215], v[66:69]
	v_mfma_f32_16x16x32_bf16 v[118:121], v[176:179], v[192:195], v[118:121]
	v_mfma_f32_16x16x32_bf16 v[114:117], v[184:187], v[192:195], v[114:117]
	v_mfma_f32_16x16x32_bf16 v[102:105], v[176:179], v[200:203], v[102:105]
	v_mfma_f32_16x16x32_bf16 v[98:101], v[184:187], v[200:203], v[98:101]
	v_mfma_f32_16x16x32_bf16 v[86:89], v[176:179], v[208:211], v[86:89]
	v_mfma_f32_16x16x32_bf16 v[82:85], v[184:187], v[208:211], v[82:85]
	v_mfma_f32_16x16x32_bf16 v[70:73], v[176:179], v[216:219], v[70:73]
	v_mfma_f32_16x16x32_bf16 v[66:69], v[184:187], v[216:219], v[66:69]
	s_setprio 0
	s_barrier
	s_add_i32 s8, s70, s45
	v_lshl_add_u64 v[138:139], v[138:139], 0, s[20:21]
	s_mov_b32 m0, s8
	ds_read_b128 v[188:191], v155 offset:49152
	ds_read_b128 v[192:195], v155 offset:50176
	ds_read_b128 v[196:199], v155 offset:51200
	ds_read_b128 v[200:203], v155 offset:52224
	ds_read_b128 v[204:207], v155 offset:53248
	ds_read_b128 v[208:211], v155 offset:54272
	ds_read_b128 v[212:215], v155 offset:55296
	ds_read_b128 v[216:219], v155 offset:56320
	global_load_lds_dwordx4 v[138:139], off
	s_add_i32 m0, s8, 0x2000
	s_add_u32 s6, s6, 0x10080
	v_lshl_add_u64 v[138:139], v[220:221], 0, s[20:21]
	s_addc_u32 s7, s7, 0
	s_add_i32 s8, s71, s45
	global_load_lds_dwordx4 v[138:139], off
	v_lshl_add_u64 v[138:139], s[6:7], 0, v[132:133]
	s_mov_b32 m0, s8
	s_nop 0
	global_load_lds_dwordx4 v[138:139], off
	v_lshl_add_u64 v[138:139], s[6:7], 0, v[136:137]
	s_add_i32 m0, s8, 0x2000
	s_nop 0
	global_load_lds_dwordx4 v[138:139], off
	v_lshl_add_u64 v[138:139], v[222:223], 0, s[20:21]
	s_mov_b32 m0, s53
	s_nop 0
	global_load_lds_dwordx4 v[138:139], off
	v_lshl_add_u64 v[138:139], v[224:225], 0, s[20:21]
	s_mov_b32 m0, s54
	s_nop 0
	global_load_lds_dwordx4 v[138:139], off
	s_waitcnt vmcnt(8)
	s_cmp_lg_u32 s12, s0
	s_cbranch_scc1 .Lmy_p8_nostat
	v_add_f32_e32 v236, v228, v229
	v_add_f32_e32 v240, v230, v231
	v_add_f32_e32 v237, v232, v233
	v_add_f32_e32 v241, v234, v235
	v_add_f32_e32 v236, v236, v240
	v_add_f32_e32 v237, v237, v241
	v_mov_b32_e32 v240, 0x20800
	v_lshl_add_u32 v240, v0, 3, v240
	ds_write_b64 v240, v[236:237]
.Lmy_p8_nostat:
	s_waitcnt lgkmcnt(0)
	s_barrier
	s_setprio 1
	s_waitcnt lgkmcnt(0)
	v_mfma_f32_16x16x32_bf16 v[62:65], v[156:159], v[188:191], v[62:65]
	v_mfma_f32_16x16x32_bf16 v[58:61], v[164:167], v[188:191], v[58:61]
	v_mfma_f32_16x16x32_bf16 v[46:49], v[156:159], v[196:199], v[46:49]
	v_mfma_f32_16x16x32_bf16 v[42:45], v[164:167], v[196:199], v[42:45]
	v_mfma_f32_16x16x32_bf16 v[30:33], v[156:159], v[204:207], v[30:33]
	v_mfma_f32_16x16x32_bf16 v[26:29], v[164:167], v[204:207], v[26:29]
	v_mfma_f32_16x16x32_bf16 v[14:17], v[156:159], v[212:215], v[14:17]
	v_mfma_f32_16x16x32_bf16 v[10:13], v[164:167], v[212:215], v[10:13]
	v_mfma_f32_16x16x32_bf16 v[62:65], v[160:163], v[192:195], v[62:65]
	v_mfma_f32_16x16x32_bf16 v[58:61], v[168:171], v[192:195], v[58:61]
	v_mfma_f32_16x16x32_bf16 v[46:49], v[160:163], v[200:203], v[46:49]
	v_mfma_f32_16x16x32_bf16 v[42:45], v[168:171], v[200:203], v[42:45]
	v_mfma_f32_16x16x32_bf16 v[30:33], v[160:163], v[208:211], v[30:33]
	v_mfma_f32_16x16x32_bf16 v[26:29], v[168:171], v[208:211], v[26:29]
	v_mfma_f32_16x16x32_bf16 v[14:17], v[160:163], v[216:219], v[14:17]
	v_mfma_f32_16x16x32_bf16 v[10:13], v[168:171], v[216:219], v[10:13]
	s_setprio 0
	s_setprio 1
	v_mfma_f32_16x16x32_bf16 v[54:57], v[172:175], v[188:191], v[54:57]
	v_mfma_f32_16x16x32_bf16 v[50:53], v[180:183], v[188:191], v[50:53]
	v_mfma_f32_16x16x32_bf16 v[38:41], v[172:175], v[196:199], v[38:41]
	v_mfma_f32_16x16x32_bf16 v[34:37], v[180:183], v[196:199], v[34:37]
	v_mfma_f32_16x16x32_bf16 v[22:25], v[172:175], v[204:207], v[22:25]
	v_mfma_f32_16x16x32_bf16 v[18:21], v[180:183], v[204:207], v[18:21]
	v_mfma_f32_16x16x32_bf16 v[6:9], v[172:175], v[212:215], v[6:9]
	v_mfma_f32_16x16x32_bf16 v[2:5], v[180:183], v[212:215], v[2:5]
	v_mfma_f32_16x16x32_bf16 v[54:57], v[176:179], v[192:195], v[54:57]
	v_mfma_f32_16x16x32_bf16 v[50:53], v[184:187], v[192:195], v[50:53]
	v_mfma_f32_16x16x32_bf16 v[38:41], v[176:179], v[200:203], v[38:41]
	v_mfma_f32_16x16x32_bf16 v[34:37], v[184:187], v[200:203], v[34:37]
	v_mfma_f32_16x16x32_bf16 v[22:25], v[176:179], v[208:211], v[22:25]
	v_mfma_f32_16x16x32_bf16 v[18:21], v[184:187], v[208:211], v[18:21]
	v_mfma_f32_16x16x32_bf16 v[6:9], v[176:179], v[216:219], v[6:9]
	v_mfma_f32_16x16x32_bf16 v[2:5], v[184:187], v[216:219], v[2:5]
	s_setprio 0
	s_barrier
	s_add_i32 s63, s63, 2
	s_add_u32 s64, s64, 0x100
	s_addc_u32 s65, s65, 0
	s_add_u32 s66, s66, 0x100
	s_addc_u32 s67, s67, 0
	s_add_u32 s0, s0, 0xffffff00
	s_addc_u32 s1, s1, -1
	v_lshl_add_u64 v[142:143], v[142:143], 0, s[24:25]
	s_cmp_gt_u32 s63, 13
	v_lshl_add_u64 v[144:145], v[144:145], 0, s[24:25]
	s_cbranch_scc0 .LBB0_971
	s_add_u32 s0, s61, 0x40080
	s_addc_u32 s1, s37, 0
	s_mov_b32 m0, s69
	v_lshl_add_u64 v[138:139], s[0:1], 0, v[130:131]
	global_load_lds_dwordx4 v[138:139], off
	v_lshl_add_u64 v[138:139], s[0:1], 0, v[134:135]
	s_mov_b32 m0, s68
	s_and_b64 vcc, exec, s[22:23]
	global_load_lds_dwordx4 v[138:139], off
	s_cbranch_vccz .LBB0_974
	s_barrier
